# static s_setprio 1 for waves 4-7 during attention phases (on top of v2)
# speedup vs baseline: 1.0105x; 1.0105x over previous
; __device__ __forceinline__ void phase_attn_even(const Params& P, unsigned char* smem) {
;   const int bid = blockIdx.x, G = gridDim.x;
;   for (int j = 0;; ++j) {
;     const int u = j * G + ((j & 1) ? (G - 1 - bid) : bid);
;     if (u >= 1024) break;
;     const int qb = 15 - (u >> 6), pr = u & 63;
;     attn_unit<0>(P, pr >> 3, pr & 7, qb, smem);
.LBB0_837:
	s_or_b64 exec, exec, s[46:47]
	s_not_b32 s6, s2
	s_add_i32 s53, s38, s6
	s_mov_b64 s[8:9], s[0:1]
	s_cmpk_gt_i32 s2, 0x3ff
	s_waitcnt lgkmcnt(0)
	s_barrier
	s_cbranch_scc1 .LBB0_880
	s_waitcnt vmcnt(0)
	v_readfirstlane_b32 s96, v254
	v_mbcnt_lo_u32_b32 v0, -1, 0
	s_nop 1
	s_lshr_b32 s96, s96, 8
	s_cmp_eq_u32 s96, 0
	s_cbranch_scc1 .Lprio_a_skip
	s_setprio 1
.Lprio_a_skip:
	s_mov_b32 s11, 0
	v_mov_b64_e32 v[138:139], s[8:9]
	s_movk_i32 s20, 0x600
	v_mov_b32_e32 v1, 0
	s_movk_i32 s21, 0x70
	s_movk_i32 s22, 0x100
	s_mov_b64 s[12:13], 0x80
	s_mov_b64 s[14:15], 0x10000
	v_mov_b32_e32 v143, 0xff800000
	v_mbcnt_hi_u32_b32 v147, -1, v0
	s_mov_b32 s6, s2
	s_mov_b32 s23, 0
	s_branch .LBB0_840

; __device__ __forceinline__ void xcd_barrier(const XcdBarrier& b) {
;     asm volatile("s_waitcnt vmcnt(0)" ::: "memory");
;     __syncthreads();
;     if (threadIdx.x == 0) {
;         unsigned* bar = b.bar;
;         __builtin_amdgcn_s_waitcnt(0);
;         unsigned nloc = b.st[0], nx = b.st[1];
;         if (nloc == 0u) { xcd_barrier_complete(bar, b.x, nloc, nx); b.st[0] = nloc; b.st[1] = nx; }
.LBB0_880:
	s_setprio 0
	s_waitcnt vmcnt(0)
	s_barrier
	s_and_saveexec_b64 s[46:47], s[4:5]
	s_cbranch_execz .LBB0_924
	s_add_i32 s6, 0, 0x20000
	s_waitcnt vmcnt(0)
	v_mov_b32_e32 v0, s6
	s_waitcnt vmcnt(0) expcnt(0) lgkmcnt(0)
	ds_read_b32 v2, v0
	s_add_i32 s6, 0, 0x20004
	v_mov_b32_e32 v0, s6
	ds_read_b32 v4, v0
	s_waitcnt lgkmcnt(1)
	v_cmp_ne_u32_e32 vcc, 0, v2
	s_cbranch_vccnz .LBB0_895
	s_load_dword s8, s[44:45], 0x14
	s_mov_b64 s[6:7], 0x1000
	v_lshl_add_u64 v[0:1], v[156:157], 0, s[6:7]
	s_mov_b64 s[6:7], 0x1100
	v_lshl_add_u64 v[2:3], v[156:157], 0, s[6:7]
	s_waitcnt lgkmcnt(0)
	s_lshr_b32 s10, s8, 16
	s_and_b32 s8, s8, 0xffff
	s_cmp_lg_u32 s8, 0
	s_cselect_b64 s[8:9], -1, 0
	s_cmp_lg_u64 s[8:9], 0
	s_addc_u32 s8, s39, 0
	s_cmp_lg_u32 s10, 0
	s_mul_i32 s24, s8, s38
	s_cselect_b64 s[8:9], -1, 0
	s_cmp_lg_u64 s[8:9], 0
	s_mov_b64 s[6:7], 0x1200
	s_addc_u32 s8, s88, 0
	v_lshl_add_u64 v[4:5], v[156:157], 0, s[6:7]
	s_mov_b64 s[6:7], 0x1300
	s_mul_i32 s24, s24, s8
	v_lshl_add_u64 v[6:7], v[156:157], 0, s[6:7]
	s_mov_b32 s25, 1
	s_mov_b64 s[6:7], 0
	s_branch .LBB0_885

; __device__ __forceinline__ void phase_attn_odd(const Params& P, unsigned char* smem) {
;   const int bid = blockIdx.x, G = gridDim.x;
;   for (int j = 0;; ++j) {
;     const int u = j * G + ((j & 1) ? (G - 1 - bid) : bid);
;     if (u >= 2048) break;
;     const int qb = 15 - (u >> 7), pr = u & 127;
;     attn_unit<1>(P, pr >> 4, pr & 15, qb, smem);
.LBB0_1607:
	s_or_b64 exec, exec, s[46:47]
	s_mov_b64 s[6:7], s[0:1]
	s_cmpk_gt_i32 s2, 0x7ff
	s_waitcnt lgkmcnt(0)
	s_barrier
	s_cbranch_scc1 .LBB0_1635
	v_readfirstlane_b32 s96, v254
	v_mbcnt_lo_u32_b32 v0, -1, 0
	s_nop 1
	s_lshr_b32 s96, s96, 8
	s_cmp_eq_u32 s96, 0
	s_cbranch_scc1 .Lprio_b_skip
	s_setprio 1
.Lprio_b_skip:
	s_mov_b32 s9, 0
	v_mov_b64_e32 v[112:113], s[6:7]
	v_mov_b32_e32 v115, 0
	s_movk_i32 s22, 0x70
	s_mov_b64 s[10:11], 0x100
	s_mov_b64 s[12:13], 0x80
	s_mov_b64 s[14:15], 0x20000
	v_mov_b32_e32 v119, 0xff800000
	v_mbcnt_hi_u32_b32 v122, -1, v0
	s_mov_b32 s24, s2
	s_mov_b32 s23, 0
	s_branch .LBB0_1610

; __device__ __forceinline__ void xcd_barrier(const XcdBarrier& b) {
;     asm volatile("s_waitcnt vmcnt(0)" ::: "memory");
;     __syncthreads();
;     if (threadIdx.x == 0) {
;         unsigned* bar = b.bar;
;         __builtin_amdgcn_s_waitcnt(0);
;         unsigned nloc = b.st[0], nx = b.st[1];
;         if (nloc == 0u) { xcd_barrier_complete(bar, b.x, nloc, nx); b.st[0] = nloc; b.st[1] = nx; }
.LBB0_1635:
	s_setprio 0
	s_waitcnt vmcnt(0)
	s_barrier
	s_and_saveexec_b64 s[46:47], s[4:5]
	s_cbranch_execz .LBB0_1679
	s_add_i32 s6, 0, 0x20000
	v_mov_b32_e32 v0, s6
	s_waitcnt vmcnt(0) expcnt(0) lgkmcnt(0)
	ds_read_b32 v2, v0
	s_add_i32 s6, 0, 0x20004
	v_mov_b32_e32 v0, s6
	ds_read_b32 v4, v0
	s_waitcnt lgkmcnt(1)
	v_cmp_ne_u32_e32 vcc, 0, v2
	s_cbranch_vccnz .LBB0_1650
	s_load_dword s8, s[44:45], 0x14
	s_mov_b64 s[6:7], 0x1000
	v_lshl_add_u64 v[0:1], v[156:157], 0, s[6:7]
	s_mov_b64 s[6:7], 0x1100
	v_lshl_add_u64 v[2:3], v[156:157], 0, s[6:7]
	s_waitcnt lgkmcnt(0)
	s_lshr_b32 s10, s8, 16
	s_and_b32 s8, s8, 0xffff
	s_cmp_lg_u32 s8, 0
	s_cselect_b64 s[8:9], -1, 0
	s_cmp_lg_u64 s[8:9], 0
	s_addc_u32 s8, s39, 0
	s_cmp_lg_u32 s10, 0
	s_mul_i32 s24, s8, s38
	s_cselect_b64 s[8:9], -1, 0
	s_cmp_lg_u64 s[8:9], 0
	s_mov_b64 s[6:7], 0x1200
	s_addc_u32 s8, s88, 0
	v_lshl_add_u64 v[4:5], v[156:157], 0, s[6:7]
	s_mov_b64 s[6:7], 0x1300
	s_mul_i32 s24, s24, s8
	v_lshl_add_u64 v[6:7], v[156:157], 0, s[6:7]
	s_mov_b32 s25, 1
	s_mov_b64 s[6:7], 0
	s_branch .LBB0_1640
